# grid-barrier atomics and polling loads issued as global_ instead of flat_ instructions
# baseline (speedup 1.0000x reference)
.LBB0_97:
	global_load_dword v25, v[0:1], off offset:1024 sc1
	global_load_dword v10, v[0:1], off offset:1280 sc1
	global_load_dword v11, v[0:1], off offset:1536 sc1
	global_load_dword v12, v[0:1], off offset:1792 sc1
	global_load_dword v13, v[0:1], off offset:2048 sc1
	global_load_dword v14, v[0:1], off offset:2304 sc1
	global_load_dword v15, v[0:1], off offset:2560 sc1
	global_load_dword v16, v[0:1], off offset:2816 sc1
	global_load_dword v17, v[0:1], off offset:3072 sc1
	global_load_dword v18, v[0:1], off offset:3328 sc1
	global_load_dword v19, v[0:1], off offset:3584 sc1
	global_load_dword v20, v[0:1], off offset:3840 sc1
	global_load_dword v21, v[2:3], off sc1
	global_load_dword v22, v[4:5], off sc1
	global_load_dword v23, v[6:7], off sc1
	global_load_dword v24, v[8:9], off sc1
	s_or_b64 s[8:9], s[8:9], exec
	s_or_b64 s[6:7], s[6:7], exec
	s_waitcnt vmcnt(0) lgkmcnt(0)
	v_add_u32_e32 v26, v10, v25
	v_add_u32_e32 v26, v26, v11
	v_add_u32_e32 v26, v26, v12
	v_add_u32_e32 v26, v26, v13
	v_add_u32_e32 v26, v26, v14
	v_add_u32_e32 v26, v26, v15
	v_add_u32_e32 v26, v26, v16
	v_add_u32_e32 v26, v26, v17
	v_add_u32_e32 v26, v26, v18
	v_add_u32_e32 v26, v26, v19
	v_add_u32_e32 v26, v26, v20
	v_add_u32_e32 v26, v26, v21
	v_add_u32_e32 v26, v26, v22
	v_add_u32_e32 v26, v26, v23
	v_add_u32_e32 v26, v26, v24
	v_cmp_ne_u32_e32 vcc, s20, v26
	s_and_saveexec_b64 s[10:11], vcc
	s_cbranch_execz .LBB0_96
	s_and_b32 s14, s21, 0xff
	s_mov_b64 s[12:13], -1
	s_cmp_eq_u32 s14, 0
	s_mov_b64 s[16:17], -1
	s_mov_b64 s[14:15], -1
	s_sleep 1
	s_cbranch_scc1 .LBB0_100
	s_and_saveexec_b64 s[18:19], s[16:17]
	s_cbranch_execz .LBB0_95
	s_branch .LBB0_103
.LBB0_100:
	global_load_dword v26, v[0:1], off offset:512 sc1
	s_mov_b64 s[16:17], 0
	s_waitcnt vmcnt(0) lgkmcnt(0)
	v_cmp_eq_u32_e32 vcc, 0, v26
	s_and_saveexec_b64 s[18:19], vcc
	s_cmp_lt_u32 s21, 0x400001
	s_cselect_b64 s[16:17], -1, 0
	s_xor_b64 s[14:15], exec, -1
	s_and_b64 s[16:17], s[16:17], exec
	s_or_b64 exec, exec, s[18:19]
	s_and_saveexec_b64 s[18:19], s[16:17]
	s_cbranch_execz .LBB0_95

.LBB0_104:
	s_or_b64 exec, exec, s[0:1]
	s_xor_b64 s[0:1], s[4:5], -1
	s_and_saveexec_b64 s[4:5], s[0:1]
	s_xor_b64 s[0:1], exec, s[4:5]
	s_cbranch_execz .LBB0_106
	v_mov_b32_e32 v2, 1
	v_mov_b64_e32 v[0:1], s[36:37]
	global_atomic_add v[0:1], v2, off offset:512

.LBB0_107:
	s_lshl_b32 s22, s33, 6
	s_add_i32 s4, s22, 0x500
	s_mov_b32 s5, 0
	s_lshl_b64 s[0:1], s[4:5], 2
	s_add_u32 s0, s36, s0
	s_addc_u32 s1, s37, s1
	v_mov_b32_e32 v1, 1
	v_mov_b64_e32 v[4:5], s[0:1]
	global_atomic_add v1, v[4:5], v1, off sc0
	v_cvt_f32_u32_e32 v3, v2
	v_sub_u32_e32 v4, 0, v2
	v_rcp_iflag_f32_e32 v3, v3
	s_nop 0
	v_mul_f32_e32 v3, 0x4f7ffffe, v3
	v_cvt_u32_f32_e32 v3, v3
	v_mul_lo_u32 v4, v4, v3
	v_mul_hi_u32 v4, v3, v4
	v_add_u32_e32 v3, v3, v4
	s_waitcnt vmcnt(0) lgkmcnt(0)
	v_mul_hi_u32 v3, v1, v3
	v_mul_lo_u32 v5, v3, v2
	v_add_u32_e32 v4, 1, v1
	v_sub_u32_e32 v1, v1, v5
	v_add_u32_e32 v6, 1, v3
	v_cmp_ge_u32_e32 vcc, v1, v2
	v_sub_u32_e32 v5, v1, v2
	s_nop 0
	v_cndmask_b32_e32 v3, v3, v6, vcc
	v_cndmask_b32_e32 v1, v1, v5, vcc
	v_add_u32_e32 v5, 1, v3
	v_cmp_ge_u32_e32 vcc, v1, v2
	s_nop 1
	v_cndmask_b32_e32 v1, v3, v5, vcc
	v_mad_u64_u32 v[2:3], s[0:1], v2, v1, v[2:3]
	v_cmp_ne_u32_e32 vcc, v4, v2
	s_and_saveexec_b64 s[0:1], vcc
	s_xor_b64 s[0:1], exec, s[0:1]
	s_cbranch_execz .LBB0_120
	s_add_i32 s4, s22, 0x900
	s_lshl_b64 s[4:5], s[4:5], 2
	s_add_u32 s6, s36, s4
	s_addc_u32 s7, s37, s5
	v_mov_b64_e32 v[2:3], s[6:7]
	buffer_inv sc1
	global_load_dword v0, v[2:3], off sc1
	s_waitcnt vmcnt(0) lgkmcnt(0)
	v_cmp_eq_u32_e32 vcc, v0, v1
	s_and_saveexec_b64 s[4:5], vcc
	s_cbranch_execz .LBB0_119
	s_mov_b32 s23, 1
	s_mov_b64 s[8:9], 0
	s_branch .LBB0_111

.LBB0_111:
	s_and_b32 s16, s23, 0xff
	s_mov_b64 s[14:15], -1
	s_cmp_lg_u32 s16, 0
	s_mov_b64 s[16:17], -1
	s_sleep 1
	s_cbranch_scc1 .LBB0_115
	v_mov_b64_e32 v[2:3], s[36:37]
	global_load_dword v0, v[2:3], off offset:512 sc1
	s_mov_b64 s[16:17], 0
	s_mov_b64 s[18:19], -1
	s_waitcnt vmcnt(0) lgkmcnt(0)
	v_cmp_eq_u32_e32 vcc, 0, v0
	s_and_saveexec_b64 s[20:21], vcc
	s_cmp_lt_u32 s23, 0x400001
	s_cselect_b64 s[16:17], -1, 0
	s_xor_b64 s[18:19], exec, -1
	s_and_b64 s[16:17], s[16:17], exec
	s_or_b64 exec, exec, s[20:21]
.LBB0_115:
	s_andn2_b64 s[12:13], s[12:13], exec
	s_and_b64 s[18:19], s[18:19], exec
	s_or_b64 s[12:13], s[12:13], s[18:19]
	s_and_saveexec_b64 s[18:19], s[16:17]
	s_cbranch_execz .LBB0_110
	v_mov_b64_e32 v[2:3], s[6:7]
	global_load_dword v0, v[2:3], off sc1
	s_add_i32 s23, s23, 1
	s_or_b64 s[12:13], s[12:13], exec
	s_waitcnt vmcnt(0) lgkmcnt(0)
	v_cmp_ne_u32_e32 vcc, v0, v1
	s_orn2_b64 s[14:15], vcc, exec
	s_branch .LBB0_110
.LBB0_117:
	s_or_b64 exec, exec, s[8:9]
	s_xor_b64 s[6:7], s[10:11], -1
	s_and_saveexec_b64 s[8:9], s[6:7]
	s_xor_b64 s[8:9], exec, s[8:9]
	s_cbranch_execz .LBB0_119
	v_mov_b32_e32 v2, 1
	v_mov_b64_e32 v[0:1], s[36:37]
	global_atomic_add v[0:1], v2, off offset:512

.LBB0_120:
	s_andn2_saveexec_b64 s[0:1], s[0:1]
	s_cbranch_execz .LBB0_137
	v_mov_b32_e32 v2, s36
	v_add_co_u32_e32 v2, vcc, 0x3000, v2
	v_mov_b32_e32 v3, s37
	buffer_wbl2 sc1
	s_waitcnt vmcnt(0) lgkmcnt(0)
	s_waitcnt vmcnt(0)
	v_addc_co_u32_e32 v3, vcc, 0, v3, vcc
	v_mov_b32_e32 v4, 1
	global_atomic_add v2, v[2:3], v4, off offset:1024 sc0
	v_cvt_f32_u32_e32 v3, v0
	v_sub_u32_e32 v4, 0, v0
	s_mov_b32 s5, 0
	v_rcp_iflag_f32_e32 v3, v3
	s_nop 0
	v_mul_f32_e32 v3, 0x4f7ffffe, v3
	v_cvt_u32_f32_e32 v3, v3
	v_mul_lo_u32 v4, v4, v3
	v_mul_hi_u32 v4, v3, v4
	v_add_u32_e32 v3, v3, v4
	s_waitcnt vmcnt(0) lgkmcnt(0)
	v_mul_hi_u32 v3, v2, v3
	v_mul_lo_u32 v5, v3, v0
	v_add_u32_e32 v4, 1, v2
	v_sub_u32_e32 v2, v2, v5
	v_add_u32_e32 v6, 1, v3
	v_cmp_ge_u32_e32 vcc, v2, v0
	v_sub_u32_e32 v5, v2, v0
	s_nop 0
	v_cndmask_b32_e32 v3, v3, v6, vcc
	v_cndmask_b32_e32 v2, v2, v5, vcc
	v_add_u32_e32 v5, 1, v3
	v_cmp_ge_u32_e32 vcc, v2, v0
	s_nop 1
	v_cndmask_b32_e32 v2, v3, v5, vcc
	v_mad_u64_u32 v[2:3], s[0:1], v0, v2, v[0:1]
	v_cmp_ne_u32_e32 vcc, v4, v2
	s_and_saveexec_b64 s[0:1], vcc
	s_xor_b64 s[0:1], exec, s[0:1]
	s_cbranch_execz .LBB0_134
	s_add_i32 s4, s22, 0x900
	s_lshl_b64 s[4:5], s[4:5], 2
	s_add_u32 s6, s36, s4
	s_addc_u32 s7, s37, s5
	v_mov_b64_e32 v[2:3], s[6:7]
	buffer_inv sc1
	global_load_dword v0, v[2:3], off sc1
	s_waitcnt vmcnt(0) lgkmcnt(0)
	v_cmp_eq_u32_e32 vcc, v0, v1
	s_and_saveexec_b64 s[4:5], vcc
	s_cbranch_execz .LBB0_133
	s_mov_b32 s22, 1
	s_mov_b64 s[8:9], 0
	s_branch .LBB0_125

.LBB0_125:
	s_and_b32 s16, s22, 0xff
	s_mov_b64 s[14:15], -1
	s_cmp_lg_u32 s16, 0
	s_mov_b64 s[16:17], -1
	s_sleep 1
	s_cbranch_scc1 .LBB0_129
	v_mov_b64_e32 v[2:3], s[36:37]
	global_load_dword v0, v[2:3], off offset:512 sc1
	s_mov_b64 s[16:17], 0
	s_mov_b64 s[18:19], -1
	s_waitcnt vmcnt(0) lgkmcnt(0)
	v_cmp_eq_u32_e32 vcc, 0, v0
	s_and_saveexec_b64 s[20:21], vcc
	s_cmp_lt_u32 s22, 0x400001
	s_cselect_b64 s[16:17], -1, 0
	s_xor_b64 s[18:19], exec, -1
	s_and_b64 s[16:17], s[16:17], exec
	s_or_b64 exec, exec, s[20:21]
.LBB0_129:
	s_andn2_b64 s[12:13], s[12:13], exec
	s_and_b64 s[18:19], s[18:19], exec
	s_or_b64 s[12:13], s[12:13], s[18:19]
	s_and_saveexec_b64 s[18:19], s[16:17]
	s_cbranch_execz .LBB0_124
	v_mov_b64_e32 v[2:3], s[6:7]
	global_load_dword v0, v[2:3], off sc1
	s_add_i32 s22, s22, 1
	s_or_b64 s[12:13], s[12:13], exec
	s_waitcnt vmcnt(0) lgkmcnt(0)
	v_cmp_ne_u32_e32 vcc, v0, v1
	s_orn2_b64 s[14:15], vcc, exec
	s_branch .LBB0_124

.LBB0_134:
	s_andn2_saveexec_b64 s[0:1], s[0:1]
	s_cbranch_execz .LBB0_136
	v_mov_b32_e32 v2, s36
	v_add_co_u32_e32 v0, vcc, 0x2000, v2
	v_mov_b32_e32 v3, s37
	s_nop 0
	v_addc_co_u32_e32 v1, vcc, 0, v3, vcc
	v_mov_b32_e32 v4, 1
	global_atomic_add v[0:1], v4, off offset:1024
	global_atomic_add v[0:1], v4, off offset:1280
	global_atomic_add v[0:1], v4, off offset:1536
	global_atomic_add v[0:1], v4, off offset:1792
	global_atomic_add v[0:1], v4, off offset:2048
	global_atomic_add v[0:1], v4, off offset:2304
	global_atomic_add v[0:1], v4, off offset:2560
	global_atomic_add v[0:1], v4, off offset:2816
	global_atomic_add v[0:1], v4, off offset:3072
	global_atomic_add v[0:1], v4, off offset:3328
	global_atomic_add v[0:1], v4, off offset:3584
	global_atomic_add v[0:1], v4, off offset:3840
	v_add_co_u32_e32 v0, vcc, 0x3000, v2
	s_nop 1
	v_addc_co_u32_e32 v1, vcc, 0, v3, vcc
	global_atomic_add v[0:1], v4, off
	global_atomic_add v[0:1], v4, off offset:256
	global_atomic_add v[0:1], v4, off offset:512
	global_atomic_add v[0:1], v4, off offset:768
	s_waitcnt vmcnt(0) lgkmcnt(0)
	buffer_inv sc1

.LBB0_157:
	s_waitcnt vmcnt(0)
	v_cmp_eq_u32_e32 vcc, 0, v131
	s_waitcnt lgkmcnt(0)
	s_barrier
	s_and_saveexec_b64 s[0:1], vcc
	s_cbranch_execz .LBB0_188
	v_readlane_b32 s2, v254, 1
	v_readlane_b32 s4, v254, 3
	v_readlane_b32 s3, v254, 2
	s_lshl_b32 s16, s4, 6
	v_readlane_b32 s5, v254, 4
	s_add_i32 s46, s16, 0x500
	s_waitcnt vmcnt(0) expcnt(0) lgkmcnt(0)
	v_mov_b32_e32 v0, s5
	s_lshl_b64 s[4:5], s[46:47], 2
	s_add_u32 s4, s2, s4
	s_addc_u32 s5, s3, s5
	v_mov_b64_e32 v[4:5], s[4:5]
	ds_read_b32 v3, v0
	ds_read_b32 v2, v0 offset:4
	global_atomic_add v4, v[4:5], v234, off sc0
	s_waitcnt lgkmcnt(0)
	v_cvt_f32_u32_e32 v0, v3
	v_sub_u32_e32 v5, 0, v3
	v_rcp_iflag_f32_e32 v0, v0
	s_nop 0
	v_mul_f32_e32 v0, 0x4f7ffffe, v0
	v_cvt_u32_f32_e32 v0, v0
	v_mul_lo_u32 v5, v5, v0
	v_mul_hi_u32 v5, v0, v5
	v_add_u32_e32 v0, v0, v5
	s_waitcnt vmcnt(0)
	v_mul_hi_u32 v0, v4, v0
	v_mul_lo_u32 v5, v0, v3
	v_sub_u32_e32 v5, v4, v5
	v_add_u32_e32 v6, 1, v0
	v_cmp_ge_u32_e32 vcc, v5, v3
	v_add_u32_e32 v4, 1, v4
	s_nop 0
	v_cndmask_b32_e32 v0, v0, v6, vcc
	v_sub_u32_e32 v6, v5, v3
	v_cndmask_b32_e32 v5, v5, v6, vcc
	v_add_u32_e32 v6, 1, v0
	v_cmp_ge_u32_e32 vcc, v5, v3
	s_nop 1
	v_cndmask_b32_e32 v0, v0, v6, vcc
	v_mul_lo_u32 v5, v3, v0
	v_add_u32_e32 v3, v5, v3
	v_cmp_ne_u32_e32 vcc, v4, v3
	s_and_saveexec_b64 s[4:5], vcc
	s_xor_b64 s[4:5], exec, s[4:5]
	s_cbranch_execz .LBB0_171
	s_add_i32 s46, s16, 0x900
	s_lshl_b64 s[6:7], s[46:47], 2
	s_add_u32 s8, s2, s6
	s_addc_u32 s9, s3, s7
	v_mov_b64_e32 v[2:3], s[8:9]
	buffer_inv sc1
	global_load_dword v2, v[2:3], off sc1
	s_waitcnt vmcnt(0) lgkmcnt(0)
	v_cmp_eq_u32_e32 vcc, v2, v0
	s_and_saveexec_b64 s[6:7], vcc
	s_cbranch_execz .LBB0_170
	s_mov_b32 s17, 1
	s_mov_b64 s[10:11], 0
	s_branch .LBB0_162

.LBB0_162:
	s_and_b32 s18, s17, 0xff
	s_mov_b64 s[20:21], -1
	s_cmp_lg_u32 s18, 0
	s_mov_b64 s[22:23], -1
	s_sleep 1
	s_cbranch_scc1 .LBB0_166
	v_mov_b64_e32 v[2:3], s[2:3]
	global_load_dword v2, v[2:3], off offset:512 sc1
	s_mov_b64 s[22:23], 0
	s_mov_b64 s[24:25], -1
	s_waitcnt vmcnt(0) lgkmcnt(0)
	v_cmp_eq_u32_e32 vcc, 0, v2
	s_and_saveexec_b64 s[26:27], vcc
	s_cmp_lt_u32 s17, 0x400001
	s_cselect_b64 s[18:19], -1, 0
	s_xor_b64 s[24:25], exec, -1
	s_and_b64 s[22:23], s[18:19], exec
	s_or_b64 exec, exec, s[26:27]
.LBB0_166:
	s_andn2_b64 s[14:15], s[14:15], exec
	s_and_b64 s[18:19], s[24:25], exec
	s_or_b64 s[14:15], s[14:15], s[18:19]
	s_and_saveexec_b64 s[24:25], s[22:23]
	s_cbranch_execz .LBB0_161
	v_mov_b64_e32 v[2:3], s[8:9]
	global_load_dword v2, v[2:3], off sc1
	s_add_i32 s17, s17, 1
	s_or_b64 s[14:15], s[14:15], exec
	s_waitcnt vmcnt(0) lgkmcnt(0)
	v_cmp_ne_u32_e32 vcc, v2, v0
	s_orn2_b64 s[20:21], vcc, exec
	s_branch .LBB0_161
.LBB0_168:
	s_or_b64 exec, exec, s[10:11]
	s_xor_b64 s[8:9], s[12:13], -1
	s_and_saveexec_b64 s[10:11], s[8:9]
	s_xor_b64 s[10:11], exec, s[10:11]
	s_cbranch_execz .LBB0_170
	v_mov_b64_e32 v[2:3], s[2:3]
	global_atomic_add v[2:3], v234, off offset:512

.LBB0_171:
	s_andn2_saveexec_b64 s[4:5], s[4:5]
	s_cbranch_execz .LBB0_188
	v_mov_b32_e32 v3, s2
	v_add_co_u32_e32 v4, vcc, 0x3000, v3
	v_mov_b32_e32 v3, s3
	buffer_wbl2 sc1
	s_waitcnt vmcnt(0) lgkmcnt(0)
	s_waitcnt vmcnt(0)
	v_addc_co_u32_e32 v5, vcc, 0, v3, vcc
	global_atomic_add v3, v[4:5], v234, off offset:1024 sc0
	v_cvt_f32_u32_e32 v4, v2
	v_sub_u32_e32 v5, 0, v2
	v_rcp_iflag_f32_e32 v4, v4
	s_nop 0
	v_mul_f32_e32 v4, 0x4f7ffffe, v4
	v_cvt_u32_f32_e32 v4, v4
	v_mul_lo_u32 v5, v5, v4
	v_mul_hi_u32 v5, v4, v5
	v_add_u32_e32 v4, v4, v5
	s_waitcnt vmcnt(0) lgkmcnt(0)
	v_mul_hi_u32 v4, v3, v4
	v_mul_lo_u32 v5, v4, v2
	v_sub_u32_e32 v5, v3, v5
	v_add_u32_e32 v6, 1, v4
	v_cmp_ge_u32_e32 vcc, v5, v2
	v_add_u32_e32 v3, 1, v3
	s_nop 0
	v_cndmask_b32_e32 v4, v4, v6, vcc
	v_sub_u32_e32 v6, v5, v2
	v_cndmask_b32_e32 v5, v5, v6, vcc
	v_add_u32_e32 v6, 1, v4
	v_cmp_ge_u32_e32 vcc, v5, v2
	s_nop 1
	v_cndmask_b32_e32 v4, v4, v6, vcc
	v_mul_lo_u32 v4, v2, v4
	v_add_u32_e32 v2, v4, v2
	v_cmp_ne_u32_e32 vcc, v3, v2
	s_and_saveexec_b64 s[4:5], vcc
	s_xor_b64 s[4:5], exec, s[4:5]
	s_cbranch_execz .LBB0_185
	s_add_i32 s46, s16, 0x900
	s_lshl_b64 s[6:7], s[46:47], 2
	s_add_u32 s8, s2, s6
	s_addc_u32 s9, s3, s7
	v_mov_b64_e32 v[2:3], s[8:9]
	buffer_inv sc1
	global_load_dword v2, v[2:3], off sc1
	s_waitcnt vmcnt(0) lgkmcnt(0)
	v_cmp_eq_u32_e32 vcc, v2, v0
	s_and_saveexec_b64 s[6:7], vcc
	s_cbranch_execz .LBB0_184
	s_mov_b32 s16, 1
	s_mov_b64 s[10:11], 0
	s_branch .LBB0_176

.LBB0_176:
	s_and_b32 s17, s16, 0xff
	s_mov_b64 s[20:21], -1
	s_cmp_lg_u32 s17, 0
	s_mov_b64 s[22:23], -1
	s_sleep 1
	s_cbranch_scc1 .LBB0_180
	v_mov_b64_e32 v[2:3], s[2:3]
	global_load_dword v2, v[2:3], off offset:512 sc1
	s_mov_b64 s[22:23], 0
	s_mov_b64 s[24:25], -1
	s_waitcnt vmcnt(0) lgkmcnt(0)
	v_cmp_eq_u32_e32 vcc, 0, v2
	s_and_saveexec_b64 s[26:27], vcc
	s_cmp_lt_u32 s16, 0x400001
	s_cselect_b64 s[18:19], -1, 0
	s_xor_b64 s[24:25], exec, -1
	s_and_b64 s[22:23], s[18:19], exec
	s_or_b64 exec, exec, s[26:27]
.LBB0_180:
	s_andn2_b64 s[14:15], s[14:15], exec
	s_and_b64 s[18:19], s[24:25], exec
	s_or_b64 s[14:15], s[14:15], s[18:19]
	s_and_saveexec_b64 s[24:25], s[22:23]
	s_cbranch_execz .LBB0_175
	v_mov_b64_e32 v[2:3], s[8:9]
	global_load_dword v2, v[2:3], off sc1
	s_add_i32 s16, s16, 1
	s_or_b64 s[14:15], s[14:15], exec
	s_waitcnt vmcnt(0) lgkmcnt(0)
	v_cmp_ne_u32_e32 vcc, v2, v0
	s_orn2_b64 s[20:21], vcc, exec
	s_branch .LBB0_175

.LBB0_185:
	s_andn2_saveexec_b64 s[4:5], s[4:5]
	s_cbranch_execz .LBB0_187
	v_mov_b32_e32 v0, s2
	v_add_co_u32_e32 v2, vcc, 0x2000, v0
	v_mov_b32_e32 v4, s3
	s_nop 0
	v_addc_co_u32_e32 v3, vcc, 0, v4, vcc
	global_atomic_add v[2:3], v234, off offset:1024
	global_atomic_add v[2:3], v234, off offset:1280
	global_atomic_add v[2:3], v234, off offset:1536
	global_atomic_add v[2:3], v234, off offset:1792
	global_atomic_add v[2:3], v234, off offset:2048
	global_atomic_add v[2:3], v234, off offset:2304
	global_atomic_add v[2:3], v234, off offset:2560
	global_atomic_add v[2:3], v234, off offset:2816
	global_atomic_add v[2:3], v234, off offset:3072
	global_atomic_add v[2:3], v234, off offset:3328
	global_atomic_add v[2:3], v234, off offset:3584
	global_atomic_add v[2:3], v234, off offset:3840
	v_add_co_u32_e32 v2, vcc, 0x3000, v0
	s_nop 1
	v_addc_co_u32_e32 v3, vcc, 0, v4, vcc
	global_atomic_add v[2:3], v234, off
	global_atomic_add v[2:3], v234, off offset:256
	global_atomic_add v[2:3], v234, off offset:512
	global_atomic_add v[2:3], v234, off offset:768
	s_waitcnt vmcnt(0) lgkmcnt(0)
	buffer_inv sc1

.LBB0_226:
	s_waitcnt vmcnt(0)
	v_cmp_eq_u32_e32 vcc, 0, v146
	s_waitcnt vmcnt(0)
	s_barrier
	s_and_saveexec_b64 s[2:3], vcc
	s_cbranch_execz .LBB0_257
	v_readlane_b32 s4, v254, 1
	v_readlane_b32 s5, v254, 2
	v_readlane_b32 s6, v254, 3
	s_lshl_b32 s16, s6, 6
	v_readlane_b32 s7, v254, 4
	s_add_i32 s46, s16, 0x500
	s_waitcnt vmcnt(0) expcnt(0) lgkmcnt(0)
	v_mov_b32_e32 v0, s7
	s_lshl_b64 s[6:7], s[46:47], 2
	s_add_u32 s6, s4, s6
	s_addc_u32 s7, s5, s7
	v_mov_b64_e32 v[4:5], s[6:7]
	ds_read_b32 v3, v0
	ds_read_b32 v2, v0 offset:4
	global_atomic_add v4, v[4:5], v234, off sc0
	s_waitcnt lgkmcnt(0)
	v_cvt_f32_u32_e32 v0, v3
	v_sub_u32_e32 v5, 0, v3
	v_rcp_iflag_f32_e32 v0, v0
	s_nop 0
	v_mul_f32_e32 v0, 0x4f7ffffe, v0
	v_cvt_u32_f32_e32 v0, v0
	v_mul_lo_u32 v5, v5, v0
	v_mul_hi_u32 v5, v0, v5
	v_add_u32_e32 v0, v0, v5
	s_waitcnt vmcnt(0)
	v_mul_hi_u32 v0, v4, v0
	v_mul_lo_u32 v5, v0, v3
	v_sub_u32_e32 v5, v4, v5
	v_add_u32_e32 v6, 1, v0
	v_cmp_ge_u32_e32 vcc, v5, v3
	v_add_u32_e32 v4, 1, v4
	s_nop 0
	v_cndmask_b32_e32 v0, v0, v6, vcc
	v_sub_u32_e32 v6, v5, v3
	v_cndmask_b32_e32 v5, v5, v6, vcc
	v_add_u32_e32 v6, 1, v0
	v_cmp_ge_u32_e32 vcc, v5, v3
	s_nop 1
	v_cndmask_b32_e32 v0, v0, v6, vcc
	v_mul_lo_u32 v5, v3, v0
	v_add_u32_e32 v3, v5, v3
	v_cmp_ne_u32_e32 vcc, v4, v3
	s_and_saveexec_b64 s[6:7], vcc
	s_xor_b64 s[6:7], exec, s[6:7]
	s_cbranch_execz .LBB0_240
	s_add_i32 s46, s16, 0x900
	s_lshl_b64 s[8:9], s[46:47], 2
	s_add_u32 s10, s4, s8
	s_addc_u32 s11, s5, s9
	v_mov_b64_e32 v[2:3], s[10:11]
	buffer_inv sc1
	global_load_dword v2, v[2:3], off sc1
	s_waitcnt vmcnt(0) lgkmcnt(0)
	v_cmp_eq_u32_e32 vcc, v2, v0
	s_and_saveexec_b64 s[8:9], vcc
	s_cbranch_execz .LBB0_239
	s_mov_b32 s17, 1
	s_mov_b64 s[12:13], 0
	s_branch .LBB0_231

.LBB0_231:
	s_and_b32 s18, s17, 0xff
	s_mov_b64 s[22:23], -1
	s_cmp_lg_u32 s18, 0
	s_mov_b64 s[24:25], -1
	s_sleep 1
	s_cbranch_scc1 .LBB0_235
	v_mov_b64_e32 v[2:3], s[4:5]
	global_load_dword v2, v[2:3], off offset:512 sc1
	s_mov_b64 s[24:25], 0
	s_mov_b64 s[26:27], -1
	s_waitcnt vmcnt(0) lgkmcnt(0)
	v_cmp_eq_u32_e32 vcc, 0, v2
	s_and_saveexec_b64 s[30:31], vcc
	s_cmp_lt_u32 s17, 0x400001
	s_cselect_b64 s[18:19], -1, 0
	s_xor_b64 s[26:27], exec, -1
	s_and_b64 s[24:25], s[18:19], exec
	s_or_b64 exec, exec, s[30:31]
.LBB0_235:
	s_andn2_b64 s[18:19], s[20:21], exec
	s_and_b64 s[20:21], s[26:27], exec
	s_or_b64 s[20:21], s[18:19], s[20:21]
	s_and_saveexec_b64 s[26:27], s[24:25]
	s_cbranch_execz .LBB0_230
	v_mov_b64_e32 v[2:3], s[10:11]
	global_load_dword v2, v[2:3], off sc1
	s_add_i32 s17, s17, 1
	s_or_b64 s[20:21], s[20:21], exec
	s_waitcnt vmcnt(0) lgkmcnt(0)
	v_cmp_ne_u32_e32 vcc, v2, v0
	s_orn2_b64 s[22:23], vcc, exec
	s_branch .LBB0_230
.LBB0_237:
	s_or_b64 exec, exec, s[12:13]
	s_xor_b64 s[10:11], s[14:15], -1
	s_and_saveexec_b64 s[12:13], s[10:11]
	s_xor_b64 s[12:13], exec, s[12:13]
	s_cbranch_execz .LBB0_239
	v_mov_b64_e32 v[2:3], s[4:5]
	global_atomic_add v[2:3], v234, off offset:512

.LBB0_240:
	s_andn2_saveexec_b64 s[6:7], s[6:7]
	s_cbranch_execz .LBB0_257
	v_mov_b32_e32 v3, s4
	v_add_co_u32_e32 v4, vcc, 0x3000, v3
	v_mov_b32_e32 v3, s5
	buffer_wbl2 sc1
	s_waitcnt vmcnt(0) lgkmcnt(0)
	s_waitcnt vmcnt(0)
	v_addc_co_u32_e32 v5, vcc, 0, v3, vcc
	global_atomic_add v3, v[4:5], v234, off offset:1024 sc0
	v_cvt_f32_u32_e32 v4, v2
	v_sub_u32_e32 v5, 0, v2
	v_rcp_iflag_f32_e32 v4, v4
	s_nop 0
	v_mul_f32_e32 v4, 0x4f7ffffe, v4
	v_cvt_u32_f32_e32 v4, v4
	v_mul_lo_u32 v5, v5, v4
	v_mul_hi_u32 v5, v4, v5
	v_add_u32_e32 v4, v4, v5
	s_waitcnt vmcnt(0) lgkmcnt(0)
	v_mul_hi_u32 v4, v3, v4
	v_mul_lo_u32 v5, v4, v2
	v_sub_u32_e32 v5, v3, v5
	v_add_u32_e32 v6, 1, v4
	v_cmp_ge_u32_e32 vcc, v5, v2
	v_add_u32_e32 v3, 1, v3
	s_nop 0
	v_cndmask_b32_e32 v4, v4, v6, vcc
	v_sub_u32_e32 v6, v5, v2
	v_cndmask_b32_e32 v5, v5, v6, vcc
	v_add_u32_e32 v6, 1, v4
	v_cmp_ge_u32_e32 vcc, v5, v2
	s_nop 1
	v_cndmask_b32_e32 v4, v4, v6, vcc
	v_mul_lo_u32 v4, v2, v4
	v_add_u32_e32 v2, v4, v2
	v_cmp_ne_u32_e32 vcc, v3, v2
	s_and_saveexec_b64 s[6:7], vcc
	s_xor_b64 s[6:7], exec, s[6:7]
	s_cbranch_execz .LBB0_254
	s_add_i32 s46, s16, 0x900
	s_lshl_b64 s[8:9], s[46:47], 2
	s_add_u32 s10, s4, s8
	s_addc_u32 s11, s5, s9
	v_mov_b64_e32 v[2:3], s[10:11]
	buffer_inv sc1
	global_load_dword v2, v[2:3], off sc1
	s_waitcnt vmcnt(0) lgkmcnt(0)
	v_cmp_eq_u32_e32 vcc, v2, v0
	s_and_saveexec_b64 s[8:9], vcc
	s_cbranch_execz .LBB0_253
	s_mov_b32 s16, 1
	s_mov_b64 s[12:13], 0
	s_branch .LBB0_245

.LBB0_245:
	s_and_b32 s17, s16, 0xff
	s_mov_b64 s[22:23], -1
	s_cmp_lg_u32 s17, 0
	s_mov_b64 s[24:25], -1
	s_sleep 1
	s_cbranch_scc1 .LBB0_249
	v_mov_b64_e32 v[2:3], s[4:5]
	global_load_dword v2, v[2:3], off offset:512 sc1
	s_mov_b64 s[24:25], 0
	s_mov_b64 s[26:27], -1
	s_waitcnt vmcnt(0) lgkmcnt(0)
	v_cmp_eq_u32_e32 vcc, 0, v2
	s_and_saveexec_b64 s[30:31], vcc
	s_cmp_lt_u32 s16, 0x400001
	s_cselect_b64 s[18:19], -1, 0
	s_xor_b64 s[26:27], exec, -1
	s_and_b64 s[24:25], s[18:19], exec
	s_or_b64 exec, exec, s[30:31]
.LBB0_249:
	s_andn2_b64 s[18:19], s[20:21], exec
	s_and_b64 s[20:21], s[26:27], exec
	s_or_b64 s[20:21], s[18:19], s[20:21]
	s_and_saveexec_b64 s[26:27], s[24:25]
	s_cbranch_execz .LBB0_244
	v_mov_b64_e32 v[2:3], s[10:11]
	global_load_dword v2, v[2:3], off sc1
	s_add_i32 s16, s16, 1
	s_or_b64 s[20:21], s[20:21], exec
	s_waitcnt vmcnt(0) lgkmcnt(0)
	v_cmp_ne_u32_e32 vcc, v2, v0
	s_orn2_b64 s[22:23], vcc, exec
	s_branch .LBB0_244

.LBB0_254:
	s_andn2_saveexec_b64 s[6:7], s[6:7]
	s_cbranch_execz .LBB0_256
	v_mov_b32_e32 v0, s4
	v_add_co_u32_e32 v2, vcc, 0x2000, v0
	v_mov_b32_e32 v4, s5
	s_nop 0
	v_addc_co_u32_e32 v3, vcc, 0, v4, vcc
	global_atomic_add v[2:3], v234, off offset:1024
	global_atomic_add v[2:3], v234, off offset:1280
	global_atomic_add v[2:3], v234, off offset:1536
	global_atomic_add v[2:3], v234, off offset:1792
	global_atomic_add v[2:3], v234, off offset:2048
	global_atomic_add v[2:3], v234, off offset:2304
	global_atomic_add v[2:3], v234, off offset:2560
	global_atomic_add v[2:3], v234, off offset:2816
	global_atomic_add v[2:3], v234, off offset:3072
	global_atomic_add v[2:3], v234, off offset:3328
	global_atomic_add v[2:3], v234, off offset:3584
	global_atomic_add v[2:3], v234, off offset:3840
	v_add_co_u32_e32 v2, vcc, 0x3000, v0
	s_nop 1
	v_addc_co_u32_e32 v3, vcc, 0, v4, vcc
	global_atomic_add v[2:3], v234, off
	global_atomic_add v[2:3], v234, off offset:256
	global_atomic_add v[2:3], v234, off offset:512
	global_atomic_add v[2:3], v234, off offset:768
	s_waitcnt vmcnt(0) lgkmcnt(0)
	buffer_inv sc1

.LBB0_305:
	s_waitcnt vmcnt(0)
	v_cmp_eq_u32_e32 vcc, 0, v75
	s_barrier
	s_and_saveexec_b64 s[0:1], vcc
	v_readlane_b32 s68, v254, 52
	v_readlane_b32 s69, v254, 53
	s_cbranch_execz .LBB0_336
	v_readlane_b32 s2, v254, 1
	v_readlane_b32 s4, v254, 3
	v_readlane_b32 s3, v254, 2
	s_lshl_b32 s16, s4, 6
	v_readlane_b32 s5, v254, 4
	s_add_i32 s46, s16, 0x500
	s_waitcnt vmcnt(0) expcnt(0) lgkmcnt(0)
	v_mov_b32_e32 v0, s5
	s_lshl_b64 s[4:5], s[46:47], 2
	s_add_u32 s4, s2, s4
	s_addc_u32 s5, s3, s5
	v_mov_b64_e32 v[4:5], s[4:5]
	ds_read_b32 v3, v0
	ds_read_b32 v2, v0 offset:4
	global_atomic_add v4, v[4:5], v234, off sc0
	s_waitcnt lgkmcnt(0)
	v_cvt_f32_u32_e32 v0, v3
	v_sub_u32_e32 v5, 0, v3
	v_rcp_iflag_f32_e32 v0, v0
	s_nop 0
	v_mul_f32_e32 v0, 0x4f7ffffe, v0
	v_cvt_u32_f32_e32 v0, v0
	v_mul_lo_u32 v5, v5, v0
	v_mul_hi_u32 v5, v0, v5
	v_add_u32_e32 v0, v0, v5
	s_waitcnt vmcnt(0)
	v_mul_hi_u32 v0, v4, v0
	v_mul_lo_u32 v5, v0, v3
	v_sub_u32_e32 v5, v4, v5
	v_add_u32_e32 v6, 1, v0
	v_cmp_ge_u32_e32 vcc, v5, v3
	v_add_u32_e32 v4, 1, v4
	s_nop 0
	v_cndmask_b32_e32 v0, v0, v6, vcc
	v_sub_u32_e32 v6, v5, v3
	v_cndmask_b32_e32 v5, v5, v6, vcc
	v_add_u32_e32 v6, 1, v0
	v_cmp_ge_u32_e32 vcc, v5, v3
	s_nop 1
	v_cndmask_b32_e32 v0, v0, v6, vcc
	v_mul_lo_u32 v5, v3, v0
	v_add_u32_e32 v3, v5, v3
	v_cmp_ne_u32_e32 vcc, v4, v3
	s_and_saveexec_b64 s[4:5], vcc
	s_xor_b64 s[4:5], exec, s[4:5]
	s_cbranch_execz .LBB0_319
	s_add_i32 s46, s16, 0x900
	s_lshl_b64 s[6:7], s[46:47], 2
	s_add_u32 s8, s2, s6
	s_addc_u32 s9, s3, s7
	v_mov_b64_e32 v[2:3], s[8:9]
	buffer_inv sc1
	global_load_dword v2, v[2:3], off sc1
	s_waitcnt vmcnt(0) lgkmcnt(0)
	v_cmp_eq_u32_e32 vcc, v2, v0
	s_and_saveexec_b64 s[6:7], vcc
	s_cbranch_execz .LBB0_318
	s_mov_b32 s17, 1
	s_mov_b64 s[10:11], 0
	s_branch .LBB0_310

.LBB0_368:
	s_waitcnt vmcnt(0)
	v_cmp_eq_u32_e32 vcc, 0, v142
	s_waitcnt vmcnt(0)
	s_barrier
	s_and_saveexec_b64 s[0:1], vcc
	s_cbranch_execz .LBB0_399
	v_readlane_b32 s2, v254, 1
	v_readlane_b32 s4, v254, 3
	v_readlane_b32 s3, v254, 2
	s_lshl_b32 s16, s4, 6
	v_readlane_b32 s5, v254, 4
	s_add_i32 s46, s16, 0x500
	s_waitcnt vmcnt(0) expcnt(0) lgkmcnt(0)
	v_mov_b32_e32 v0, s5
	s_lshl_b64 s[4:5], s[46:47], 2
	s_add_u32 s4, s2, s4
	s_addc_u32 s5, s3, s5
	v_mov_b64_e32 v[4:5], s[4:5]
	ds_read_b32 v3, v0
	ds_read_b32 v2, v0 offset:4
	global_atomic_add v4, v[4:5], v234, off sc0
	s_waitcnt lgkmcnt(0)
	v_cvt_f32_u32_e32 v0, v3
	v_sub_u32_e32 v5, 0, v3
	v_rcp_iflag_f32_e32 v0, v0
	s_nop 0
	v_mul_f32_e32 v0, 0x4f7ffffe, v0
	v_cvt_u32_f32_e32 v0, v0
	v_mul_lo_u32 v5, v5, v0
	v_mul_hi_u32 v5, v0, v5
	v_add_u32_e32 v0, v0, v5
	s_waitcnt vmcnt(0)
	v_mul_hi_u32 v0, v4, v0
	v_mul_lo_u32 v5, v0, v3
	v_sub_u32_e32 v5, v4, v5
	v_add_u32_e32 v6, 1, v0
	v_cmp_ge_u32_e32 vcc, v5, v3
	v_add_u32_e32 v4, 1, v4
	s_nop 0
	v_cndmask_b32_e32 v0, v0, v6, vcc
	v_sub_u32_e32 v6, v5, v3
	v_cndmask_b32_e32 v5, v5, v6, vcc
	v_add_u32_e32 v6, 1, v0
	v_cmp_ge_u32_e32 vcc, v5, v3
	s_nop 1
	v_cndmask_b32_e32 v0, v0, v6, vcc
	v_mul_lo_u32 v5, v3, v0
	v_add_u32_e32 v3, v5, v3
	v_cmp_ne_u32_e32 vcc, v4, v3
	s_and_saveexec_b64 s[4:5], vcc
	s_xor_b64 s[4:5], exec, s[4:5]
	s_cbranch_execz .LBB0_382
	s_add_i32 s46, s16, 0x900
	s_lshl_b64 s[6:7], s[46:47], 2
	s_add_u32 s8, s2, s6
	s_addc_u32 s9, s3, s7
	v_mov_b64_e32 v[2:3], s[8:9]
	buffer_inv sc1
	global_load_dword v2, v[2:3], off sc1
	s_waitcnt vmcnt(0) lgkmcnt(0)
	v_cmp_eq_u32_e32 vcc, v2, v0
	s_and_saveexec_b64 s[6:7], vcc
	s_cbranch_execz .LBB0_381
	s_mov_b32 s17, 1
	s_mov_b64 s[10:11], 0
	s_branch .LBB0_373

.LBB0_583:
	s_waitcnt vmcnt(0)
	v_cmp_eq_u32_e32 vcc, 0, v168
	s_waitcnt lgkmcnt(0)
	s_barrier
	s_and_saveexec_b64 s[0:1], vcc
	v_readlane_b32 s82, v254, 36
	v_readlane_b32 s58, v254, 40
	v_readlane_b32 s28, v254, 30
	v_readlane_b32 s83, v254, 37
	v_readlane_b32 s59, v254, 41
	v_readlane_b32 s29, v254, 31
	s_cbranch_execz .LBB0_614
	v_readlane_b32 s2, v254, 1
	v_readlane_b32 s4, v254, 3
	v_readlane_b32 s3, v254, 2
	s_lshl_b32 s16, s4, 6
	v_readlane_b32 s5, v254, 4
	s_add_i32 s46, s16, 0x500
	s_waitcnt vmcnt(0) expcnt(0) lgkmcnt(0)
	v_mov_b32_e32 v0, s5
	s_lshl_b64 s[4:5], s[46:47], 2
	s_add_u32 s4, s2, s4
	s_addc_u32 s5, s3, s5
	v_mov_b64_e32 v[4:5], s[4:5]
	ds_read_b32 v3, v0
	ds_read_b32 v2, v0 offset:4
	global_atomic_add v4, v[4:5], v234, off sc0
	s_waitcnt lgkmcnt(0)
	v_cvt_f32_u32_e32 v0, v3
	v_sub_u32_e32 v5, 0, v3
	v_rcp_iflag_f32_e32 v0, v0
	s_nop 0
	v_mul_f32_e32 v0, 0x4f7ffffe, v0
	v_cvt_u32_f32_e32 v0, v0
	v_mul_lo_u32 v5, v5, v0
	v_mul_hi_u32 v5, v0, v5
	v_add_u32_e32 v0, v0, v5
	s_waitcnt vmcnt(0)
	v_mul_hi_u32 v0, v4, v0
	v_mul_lo_u32 v5, v0, v3
	v_sub_u32_e32 v5, v4, v5
	v_add_u32_e32 v6, 1, v0
	v_cmp_ge_u32_e32 vcc, v5, v3
	v_add_u32_e32 v4, 1, v4
	s_nop 0
	v_cndmask_b32_e32 v0, v0, v6, vcc
	v_sub_u32_e32 v6, v5, v3
	v_cndmask_b32_e32 v5, v5, v6, vcc
	v_add_u32_e32 v6, 1, v0
	v_cmp_ge_u32_e32 vcc, v5, v3
	s_nop 1
	v_cndmask_b32_e32 v0, v0, v6, vcc
	v_mul_lo_u32 v5, v3, v0
	v_add_u32_e32 v3, v5, v3
	v_cmp_ne_u32_e32 vcc, v4, v3
	s_and_saveexec_b64 s[4:5], vcc
	s_xor_b64 s[4:5], exec, s[4:5]
	s_cbranch_execz .LBB0_597
	s_add_i32 s46, s16, 0x900
	s_lshl_b64 s[6:7], s[46:47], 2
	s_add_u32 s8, s2, s6
	s_addc_u32 s9, s3, s7
	v_mov_b64_e32 v[2:3], s[8:9]
	buffer_inv sc1
	global_load_dword v2, v[2:3], off sc1
	s_waitcnt vmcnt(0) lgkmcnt(0)
	v_cmp_eq_u32_e32 vcc, v2, v0
	s_and_saveexec_b64 s[6:7], vcc
	s_cbranch_execz .LBB0_596
	s_mov_b32 s17, 1
	s_mov_b64 s[10:11], 0
	s_branch .LBB0_588

.LBB0_617:
	s_waitcnt vmcnt(0)
	v_cmp_eq_u32_e32 vcc, 0, v16
	s_barrier
	s_and_saveexec_b64 s[0:1], vcc
	s_cbranch_execz .LBB0_648
	v_readlane_b32 s2, v254, 1
	v_readlane_b32 s4, v254, 3
	v_readlane_b32 s3, v254, 2
	s_lshl_b32 s16, s4, 6
	v_readlane_b32 s5, v254, 4
	s_add_i32 s46, s16, 0x500
	s_waitcnt vmcnt(0) expcnt(0) lgkmcnt(0)
	v_mov_b32_e32 v0, s5
	s_lshl_b64 s[4:5], s[46:47], 2
	s_add_u32 s4, s2, s4
	s_addc_u32 s5, s3, s5
	v_mov_b64_e32 v[4:5], s[4:5]
	ds_read_b32 v3, v0
	ds_read_b32 v2, v0 offset:4
	global_atomic_add v4, v[4:5], v234, off sc0
	s_waitcnt lgkmcnt(0)
	v_cvt_f32_u32_e32 v0, v3
	v_sub_u32_e32 v5, 0, v3
	v_rcp_iflag_f32_e32 v0, v0
	s_nop 0
	v_mul_f32_e32 v0, 0x4f7ffffe, v0
	v_cvt_u32_f32_e32 v0, v0
	v_mul_lo_u32 v5, v5, v0
	v_mul_hi_u32 v5, v0, v5
	v_add_u32_e32 v0, v0, v5
	s_waitcnt vmcnt(0)
	v_mul_hi_u32 v0, v4, v0
	v_mul_lo_u32 v5, v0, v3
	v_sub_u32_e32 v5, v4, v5
	v_add_u32_e32 v6, 1, v0
	v_cmp_ge_u32_e32 vcc, v5, v3
	v_add_u32_e32 v4, 1, v4
	s_nop 0
	v_cndmask_b32_e32 v0, v0, v6, vcc
	v_sub_u32_e32 v6, v5, v3
	v_cndmask_b32_e32 v5, v5, v6, vcc
	v_add_u32_e32 v6, 1, v0
	v_cmp_ge_u32_e32 vcc, v5, v3
	s_nop 1
	v_cndmask_b32_e32 v0, v0, v6, vcc
	v_mul_lo_u32 v5, v3, v0
	v_add_u32_e32 v3, v5, v3
	v_cmp_ne_u32_e32 vcc, v4, v3
	s_and_saveexec_b64 s[4:5], vcc
	s_xor_b64 s[4:5], exec, s[4:5]
	s_cbranch_execz .LBB0_631
	s_add_i32 s46, s16, 0x900
	s_lshl_b64 s[6:7], s[46:47], 2
	s_add_u32 s8, s2, s6
	s_addc_u32 s9, s3, s7
	v_mov_b64_e32 v[2:3], s[8:9]
	buffer_inv sc1
	global_load_dword v2, v[2:3], off sc1
	s_waitcnt vmcnt(0) lgkmcnt(0)
	v_cmp_eq_u32_e32 vcc, v2, v0
	s_and_saveexec_b64 s[6:7], vcc
	s_cbranch_execz .LBB0_630
	s_mov_b32 s17, 1
	s_mov_b64 s[10:11], 0
	s_branch .LBB0_622

.LBB0_681:
	s_waitcnt vmcnt(0)
	v_cmp_eq_u32_e32 vcc, 0, v27
	s_barrier
	s_and_saveexec_b64 s[0:1], vcc
	s_cbranch_execz .LBB0_712
	v_readlane_b32 s2, v254, 1
	v_readlane_b32 s4, v254, 3
	v_readlane_b32 s3, v254, 2
	s_lshl_b32 s16, s4, 6
	v_readlane_b32 s5, v254, 4
	s_add_i32 s46, s16, 0x500
	s_waitcnt vmcnt(0) expcnt(0) lgkmcnt(0)
	v_mov_b32_e32 v0, s5
	s_lshl_b64 s[4:5], s[46:47], 2
	s_add_u32 s4, s2, s4
	s_addc_u32 s5, s3, s5
	v_mov_b64_e32 v[4:5], s[4:5]
	ds_read_b32 v3, v0
	ds_read_b32 v2, v0 offset:4
	global_atomic_add v4, v[4:5], v234, off sc0
	s_waitcnt lgkmcnt(0)
	v_cvt_f32_u32_e32 v0, v3
	v_sub_u32_e32 v5, 0, v3
	v_rcp_iflag_f32_e32 v0, v0
	s_nop 0
	v_mul_f32_e32 v0, 0x4f7ffffe, v0
	v_cvt_u32_f32_e32 v0, v0
	v_mul_lo_u32 v5, v5, v0
	v_mul_hi_u32 v5, v0, v5
	v_add_u32_e32 v0, v0, v5
	s_waitcnt vmcnt(0)
	v_mul_hi_u32 v0, v4, v0
	v_mul_lo_u32 v5, v0, v3
	v_sub_u32_e32 v5, v4, v5
	v_add_u32_e32 v6, 1, v0
	v_cmp_ge_u32_e32 vcc, v5, v3
	v_add_u32_e32 v4, 1, v4
	s_nop 0
	v_cndmask_b32_e32 v0, v0, v6, vcc
	v_sub_u32_e32 v6, v5, v3
	v_cndmask_b32_e32 v5, v5, v6, vcc
	v_add_u32_e32 v6, 1, v0
	v_cmp_ge_u32_e32 vcc, v5, v3
	s_nop 1
	v_cndmask_b32_e32 v0, v0, v6, vcc
	v_mul_lo_u32 v5, v3, v0
	v_add_u32_e32 v3, v5, v3
	v_cmp_ne_u32_e32 vcc, v4, v3
	s_and_saveexec_b64 s[4:5], vcc
	s_xor_b64 s[4:5], exec, s[4:5]
	s_cbranch_execz .LBB0_695
	s_add_i32 s46, s16, 0x900
	s_lshl_b64 s[6:7], s[46:47], 2
	s_add_u32 s8, s2, s6
	s_addc_u32 s9, s3, s7
	v_mov_b64_e32 v[2:3], s[8:9]
	buffer_inv sc1
	global_load_dword v2, v[2:3], off sc1
	s_waitcnt vmcnt(0) lgkmcnt(0)
	v_cmp_eq_u32_e32 vcc, v2, v0
	s_and_saveexec_b64 s[6:7], vcc
	s_cbranch_execz .LBB0_694
	s_mov_b32 s17, 1
	s_mov_b64 s[10:11], 0
	s_branch .LBB0_686

.LBB0_908:
	s_waitcnt vmcnt(0)
	v_cmp_eq_u32_e32 vcc, 0, v164
	s_waitcnt lgkmcnt(0)
	s_barrier
	s_and_saveexec_b64 s[0:1], vcc
	s_cbranch_execz .LBB0_939
	v_readlane_b32 s2, v254, 1
	v_readlane_b32 s4, v254, 3
	v_readlane_b32 s3, v254, 2
	s_lshl_b32 s16, s4, 6
	v_readlane_b32 s5, v254, 4
	s_add_i32 s46, s16, 0x500
	s_waitcnt vmcnt(0) expcnt(0) lgkmcnt(0)
	v_mov_b32_e32 v0, s5
	s_lshl_b64 s[4:5], s[46:47], 2
	s_add_u32 s4, s2, s4
	s_addc_u32 s5, s3, s5
	v_mov_b64_e32 v[4:5], s[4:5]
	ds_read_b32 v3, v0
	ds_read_b32 v2, v0 offset:4
	global_atomic_add v4, v[4:5], v234, off sc0
	s_waitcnt lgkmcnt(0)
	v_cvt_f32_u32_e32 v0, v3
	v_sub_u32_e32 v5, 0, v3
	v_rcp_iflag_f32_e32 v0, v0
	s_nop 0
	v_mul_f32_e32 v0, 0x4f7ffffe, v0
	v_cvt_u32_f32_e32 v0, v0
	v_mul_lo_u32 v5, v5, v0
	v_mul_hi_u32 v5, v0, v5
	v_add_u32_e32 v0, v0, v5
	s_waitcnt vmcnt(0)
	v_mul_hi_u32 v0, v4, v0
	v_mul_lo_u32 v5, v0, v3
	v_sub_u32_e32 v5, v4, v5
	v_add_u32_e32 v6, 1, v0
	v_cmp_ge_u32_e32 vcc, v5, v3
	v_add_u32_e32 v4, 1, v4
	s_nop 0
	v_cndmask_b32_e32 v0, v0, v6, vcc
	v_sub_u32_e32 v6, v5, v3
	v_cndmask_b32_e32 v5, v5, v6, vcc
	v_add_u32_e32 v6, 1, v0
	v_cmp_ge_u32_e32 vcc, v5, v3
	s_nop 1
	v_cndmask_b32_e32 v0, v0, v6, vcc
	v_mul_lo_u32 v5, v3, v0
	v_add_u32_e32 v3, v5, v3
	v_cmp_ne_u32_e32 vcc, v4, v3
	s_and_saveexec_b64 s[4:5], vcc
	s_xor_b64 s[4:5], exec, s[4:5]
	s_cbranch_execz .LBB0_922
	s_add_i32 s46, s16, 0x900
	s_lshl_b64 s[6:7], s[46:47], 2
	s_add_u32 s8, s2, s6
	s_addc_u32 s9, s3, s7
	v_mov_b64_e32 v[2:3], s[8:9]
	buffer_inv sc1
	global_load_dword v2, v[2:3], off sc1
	s_waitcnt vmcnt(0) lgkmcnt(0)
	v_cmp_eq_u32_e32 vcc, v2, v0
	s_and_saveexec_b64 s[6:7], vcc
	s_cbranch_execz .LBB0_921
	s_mov_b32 s17, 1
	s_mov_b64 s[10:11], 0
	s_branch .LBB0_913

.LBB0_992:
	s_waitcnt vmcnt(0)
	v_cmp_eq_u32_e32 vcc, 0, v190
	s_waitcnt vmcnt(0) lgkmcnt(0)
	s_barrier
	s_and_saveexec_b64 s[0:1], vcc
	s_cbranch_execz .LBB0_1023
	v_readlane_b32 s2, v254, 1
	v_readlane_b32 s4, v254, 3
	v_readlane_b32 s3, v254, 2
	s_lshl_b32 s16, s4, 6
	v_readlane_b32 s5, v254, 4
	s_add_i32 s46, s16, 0x500
	s_waitcnt vmcnt(0) expcnt(0) lgkmcnt(0)
	v_mov_b32_e32 v0, s5
	s_lshl_b64 s[4:5], s[46:47], 2
	s_add_u32 s4, s2, s4
	s_addc_u32 s5, s3, s5
	v_mov_b64_e32 v[4:5], s[4:5]
	ds_read_b32 v3, v0
	ds_read_b32 v2, v0 offset:4
	global_atomic_add v4, v[4:5], v234, off sc0
	s_waitcnt lgkmcnt(0)
	v_cvt_f32_u32_e32 v0, v3
	v_sub_u32_e32 v5, 0, v3
	v_rcp_iflag_f32_e32 v0, v0
	s_nop 0
	v_mul_f32_e32 v0, 0x4f7ffffe, v0
	v_cvt_u32_f32_e32 v0, v0
	v_mul_lo_u32 v5, v5, v0
	v_mul_hi_u32 v5, v0, v5
	v_add_u32_e32 v0, v0, v5
	s_waitcnt vmcnt(0)
	v_mul_hi_u32 v0, v4, v0
	v_mul_lo_u32 v5, v0, v3
	v_sub_u32_e32 v5, v4, v5
	v_add_u32_e32 v6, 1, v0
	v_cmp_ge_u32_e32 vcc, v5, v3
	v_add_u32_e32 v4, 1, v4
	s_nop 0
	v_cndmask_b32_e32 v0, v0, v6, vcc
	v_sub_u32_e32 v6, v5, v3
	v_cndmask_b32_e32 v5, v5, v6, vcc
	v_add_u32_e32 v6, 1, v0
	v_cmp_ge_u32_e32 vcc, v5, v3
	s_nop 1
	v_cndmask_b32_e32 v0, v0, v6, vcc
	v_mul_lo_u32 v5, v3, v0
	v_add_u32_e32 v3, v5, v3
	v_cmp_ne_u32_e32 vcc, v4, v3
	s_and_saveexec_b64 s[4:5], vcc
	s_xor_b64 s[4:5], exec, s[4:5]
	s_cbranch_execz .LBB0_1006
	s_add_i32 s46, s16, 0x900
	s_lshl_b64 s[6:7], s[46:47], 2
	s_add_u32 s8, s2, s6
	s_addc_u32 s9, s3, s7
	v_mov_b64_e32 v[2:3], s[8:9]
	buffer_inv sc1
	global_load_dword v2, v[2:3], off sc1
	s_waitcnt vmcnt(0) lgkmcnt(0)
	v_cmp_eq_u32_e32 vcc, v2, v0
	s_and_saveexec_b64 s[6:7], vcc
	s_cbranch_execz .LBB0_1005
	s_mov_b32 s17, 1
	s_mov_b64 s[10:11], 0
	s_branch .LBB0_997

.LBB0_1038:
	s_waitcnt vmcnt(0)
	v_cmp_eq_u32_e32 vcc, 0, v131
	s_waitcnt lgkmcnt(0)
	s_barrier
	s_and_saveexec_b64 s[0:1], vcc
	s_cbranch_execz .LBB0_1069
	v_readlane_b32 s2, v254, 1
	v_readlane_b32 s4, v254, 3
	v_readlane_b32 s3, v254, 2
	s_lshl_b32 s18, s4, 6
	v_readlane_b32 s5, v254, 4
	s_add_i32 s46, s18, 0x500
	s_waitcnt vmcnt(0) expcnt(0) lgkmcnt(0)
	v_mov_b32_e32 v0, s5
	s_lshl_b64 s[4:5], s[46:47], 2
	s_add_u32 s4, s2, s4
	s_addc_u32 s5, s3, s5
	v_mov_b64_e32 v[4:5], s[4:5]
	ds_read_b32 v3, v0
	ds_read_b32 v2, v0 offset:4
	global_atomic_add v4, v[4:5], v234, off sc0
	s_waitcnt lgkmcnt(0)
	v_cvt_f32_u32_e32 v0, v3
	v_sub_u32_e32 v5, 0, v3
	v_rcp_iflag_f32_e32 v0, v0
	s_nop 0
	v_mul_f32_e32 v0, 0x4f7ffffe, v0
	v_cvt_u32_f32_e32 v0, v0
	v_mul_lo_u32 v5, v5, v0
	v_mul_hi_u32 v5, v0, v5
	v_add_u32_e32 v0, v0, v5
	s_waitcnt vmcnt(0)
	v_mul_hi_u32 v0, v4, v0
	v_mul_lo_u32 v5, v0, v3
	v_sub_u32_e32 v5, v4, v5
	v_add_u32_e32 v6, 1, v0
	v_cmp_ge_u32_e32 vcc, v5, v3
	v_add_u32_e32 v4, 1, v4
	s_nop 0
	v_cndmask_b32_e32 v0, v0, v6, vcc
	v_sub_u32_e32 v6, v5, v3
	v_cndmask_b32_e32 v5, v5, v6, vcc
	v_add_u32_e32 v6, 1, v0
	v_cmp_ge_u32_e32 vcc, v5, v3
	s_nop 1
	v_cndmask_b32_e32 v0, v0, v6, vcc
	v_mul_lo_u32 v5, v3, v0
	v_add_u32_e32 v3, v5, v3
	v_cmp_ne_u32_e32 vcc, v4, v3
	s_and_saveexec_b64 s[4:5], vcc
	s_xor_b64 s[4:5], exec, s[4:5]
	s_cbranch_execz .LBB0_1052
	s_add_i32 s46, s18, 0x900
	s_lshl_b64 s[6:7], s[46:47], 2
	s_add_u32 s8, s2, s6
	s_addc_u32 s9, s3, s7
	v_mov_b64_e32 v[2:3], s[8:9]
	buffer_inv sc1
	global_load_dword v2, v[2:3], off sc1
	s_waitcnt vmcnt(0) lgkmcnt(0)
	v_cmp_eq_u32_e32 vcc, v2, v0
	s_and_saveexec_b64 s[6:7], vcc
	s_cbranch_execz .LBB0_1051
	s_mov_b32 s19, 1
	s_mov_b64 s[10:11], 0
	s_branch .LBB0_1043

.LBB0_1043:
	s_and_b32 s20, s19, 0xff
	s_mov_b64 s[16:17], -1
	s_cmp_lg_u32 s20, 0
	s_mov_b64 s[20:21], -1
	s_sleep 1
	s_cbranch_scc1 .LBB0_1047
	v_mov_b64_e32 v[2:3], s[2:3]
	global_load_dword v2, v[2:3], off offset:512 sc1
	s_mov_b64 s[20:21], 0
	s_mov_b64 s[22:23], -1
	s_waitcnt vmcnt(0) lgkmcnt(0)
	v_cmp_eq_u32_e32 vcc, 0, v2
	s_and_saveexec_b64 s[24:25], vcc
	s_cmp_lt_u32 s19, 0x400001
	s_cselect_b64 s[20:21], -1, 0
	s_xor_b64 s[22:23], exec, -1
	s_and_b64 s[20:21], s[20:21], exec
	s_or_b64 exec, exec, s[24:25]
.LBB0_1047:
	s_andn2_b64 s[14:15], s[14:15], exec
	s_and_b64 s[22:23], s[22:23], exec
	s_or_b64 s[14:15], s[14:15], s[22:23]
	s_and_saveexec_b64 s[22:23], s[20:21]
	s_cbranch_execz .LBB0_1042
	v_mov_b64_e32 v[2:3], s[8:9]
	global_load_dword v2, v[2:3], off sc1
	s_add_i32 s19, s19, 1
	s_or_b64 s[14:15], s[14:15], exec
	s_waitcnt vmcnt(0) lgkmcnt(0)
	v_cmp_ne_u32_e32 vcc, v2, v0
	s_orn2_b64 s[16:17], vcc, exec
	s_branch .LBB0_1042

.LBB0_1052:
	s_andn2_saveexec_b64 s[4:5], s[4:5]
	s_cbranch_execz .LBB0_1069
	v_mov_b32_e32 v3, s2
	v_add_co_u32_e32 v4, vcc, 0x3000, v3
	v_mov_b32_e32 v3, s3
	buffer_wbl2 sc1
	s_waitcnt vmcnt(0) lgkmcnt(0)
	s_waitcnt vmcnt(0)
	v_addc_co_u32_e32 v5, vcc, 0, v3, vcc
	global_atomic_add v3, v[4:5], v234, off offset:1024 sc0
	v_cvt_f32_u32_e32 v4, v2
	v_sub_u32_e32 v5, 0, v2
	v_rcp_iflag_f32_e32 v4, v4
	s_nop 0
	v_mul_f32_e32 v4, 0x4f7ffffe, v4
	v_cvt_u32_f32_e32 v4, v4
	v_mul_lo_u32 v5, v5, v4
	v_mul_hi_u32 v5, v4, v5
	v_add_u32_e32 v4, v4, v5
	s_waitcnt vmcnt(0) lgkmcnt(0)
	v_mul_hi_u32 v4, v3, v4
	v_mul_lo_u32 v5, v4, v2
	v_sub_u32_e32 v5, v3, v5
	v_add_u32_e32 v6, 1, v4
	v_cmp_ge_u32_e32 vcc, v5, v2
	v_add_u32_e32 v3, 1, v3
	s_nop 0
	v_cndmask_b32_e32 v4, v4, v6, vcc
	v_sub_u32_e32 v6, v5, v2
	v_cndmask_b32_e32 v5, v5, v6, vcc
	v_add_u32_e32 v6, 1, v4
	v_cmp_ge_u32_e32 vcc, v5, v2
	s_nop 1
	v_cndmask_b32_e32 v4, v4, v6, vcc
	v_mul_lo_u32 v4, v2, v4
	v_add_u32_e32 v2, v4, v2
	v_cmp_ne_u32_e32 vcc, v3, v2
	s_and_saveexec_b64 s[4:5], vcc
	s_xor_b64 s[4:5], exec, s[4:5]
	s_cbranch_execz .LBB0_1066
	s_add_i32 s46, s18, 0x900
	s_lshl_b64 s[6:7], s[46:47], 2
	s_add_u32 s8, s2, s6
	s_addc_u32 s9, s3, s7
	v_mov_b64_e32 v[2:3], s[8:9]
	buffer_inv sc1
	global_load_dword v2, v[2:3], off sc1
	s_waitcnt vmcnt(0) lgkmcnt(0)
	v_cmp_eq_u32_e32 vcc, v2, v0
	s_and_saveexec_b64 s[6:7], vcc
	s_cbranch_execz .LBB0_1065
	s_mov_b32 s18, 1
	s_mov_b64 s[10:11], 0
	s_branch .LBB0_1057

.LBB0_1057:
	s_and_b32 s19, s18, 0xff
	s_mov_b64 s[16:17], -1
	s_cmp_lg_u32 s19, 0
	s_mov_b64 s[20:21], -1
	s_sleep 1
	s_cbranch_scc1 .LBB0_1061
	v_mov_b64_e32 v[2:3], s[2:3]
	global_load_dword v2, v[2:3], off offset:512 sc1
	s_mov_b64 s[20:21], 0
	s_mov_b64 s[22:23], -1
	s_waitcnt vmcnt(0) lgkmcnt(0)
	v_cmp_eq_u32_e32 vcc, 0, v2
	s_and_saveexec_b64 s[24:25], vcc
	s_cmp_lt_u32 s18, 0x400001
	s_cselect_b64 s[20:21], -1, 0
	s_xor_b64 s[22:23], exec, -1
	s_and_b64 s[20:21], s[20:21], exec
	s_or_b64 exec, exec, s[24:25]
.LBB0_1061:
	s_andn2_b64 s[14:15], s[14:15], exec
	s_and_b64 s[22:23], s[22:23], exec
	s_or_b64 s[14:15], s[14:15], s[22:23]
	s_and_saveexec_b64 s[22:23], s[20:21]
	s_cbranch_execz .LBB0_1056
	v_mov_b64_e32 v[2:3], s[8:9]
	global_load_dword v2, v[2:3], off sc1
	s_add_i32 s18, s18, 1
	s_or_b64 s[14:15], s[14:15], exec
	s_waitcnt vmcnt(0) lgkmcnt(0)
	v_cmp_ne_u32_e32 vcc, v2, v0
	s_orn2_b64 s[16:17], vcc, exec
	s_branch .LBB0_1056

.LBB0_1103:
	s_waitcnt vmcnt(0)
	v_cmp_eq_u32_e32 vcc, 0, v222
	s_waitcnt lgkmcnt(0)
	s_barrier
	s_and_saveexec_b64 s[4:5], vcc
	s_cbranch_execz .LBB0_1134
	v_readlane_b32 s6, v254, 1
	v_readlane_b32 s8, v254, 3
	v_readlane_b32 s7, v254, 2
	s_lshl_b32 s18, s8, 6
	v_readlane_b32 s9, v254, 4
	s_add_i32 s46, s18, 0x500
	s_waitcnt vmcnt(0) expcnt(0) lgkmcnt(0)
	v_mov_b32_e32 v0, s9
	s_lshl_b64 s[8:9], s[46:47], 2
	s_add_u32 s8, s6, s8
	s_addc_u32 s9, s7, s9
	v_mov_b64_e32 v[4:5], s[8:9]
	ds_read_b32 v3, v0
	ds_read_b32 v2, v0 offset:4
	global_atomic_add v4, v[4:5], v234, off sc0
	s_waitcnt lgkmcnt(0)
	v_cvt_f32_u32_e32 v0, v3
	v_sub_u32_e32 v5, 0, v3
	v_rcp_iflag_f32_e32 v0, v0
	s_nop 0
	v_mul_f32_e32 v0, 0x4f7ffffe, v0
	v_cvt_u32_f32_e32 v0, v0
	v_mul_lo_u32 v5, v5, v0
	v_mul_hi_u32 v5, v0, v5
	v_add_u32_e32 v0, v0, v5
	s_waitcnt vmcnt(0)
	v_mul_hi_u32 v0, v4, v0
	v_mul_lo_u32 v5, v0, v3
	v_sub_u32_e32 v5, v4, v5
	v_add_u32_e32 v6, 1, v0
	v_cmp_ge_u32_e32 vcc, v5, v3
	v_add_u32_e32 v4, 1, v4
	s_nop 0
	v_cndmask_b32_e32 v0, v0, v6, vcc
	v_sub_u32_e32 v6, v5, v3
	v_cndmask_b32_e32 v5, v5, v6, vcc
	v_add_u32_e32 v6, 1, v0
	v_cmp_ge_u32_e32 vcc, v5, v3
	s_nop 1
	v_cndmask_b32_e32 v0, v0, v6, vcc
	v_mul_lo_u32 v5, v3, v0
	v_add_u32_e32 v3, v5, v3
	v_cmp_ne_u32_e32 vcc, v4, v3
	s_and_saveexec_b64 s[8:9], vcc
	s_xor_b64 s[8:9], exec, s[8:9]
	s_cbranch_execz .LBB0_1117
	s_add_i32 s46, s18, 0x900
	s_lshl_b64 s[10:11], s[46:47], 2
	s_add_u32 s12, s6, s10
	s_addc_u32 s13, s7, s11
	v_mov_b64_e32 v[2:3], s[12:13]
	buffer_inv sc1
	global_load_dword v2, v[2:3], off sc1
	s_waitcnt vmcnt(0) lgkmcnt(0)
	v_cmp_eq_u32_e32 vcc, v2, v0
	s_and_saveexec_b64 s[10:11], vcc
	s_cbranch_execz .LBB0_1116
	s_mov_b32 s19, 1
	s_mov_b64 s[14:15], 0
	s_branch .LBB0_1108

.LBB0_1108:
	s_and_b32 s24, s19, 0xff
	s_mov_b64 s[22:23], -1
	s_cmp_lg_u32 s24, 0
	s_mov_b64 s[24:25], -1
	s_sleep 1
	s_cbranch_scc1 .LBB0_1112
	v_mov_b64_e32 v[2:3], s[6:7]
	global_load_dword v2, v[2:3], off offset:512 sc1
	s_mov_b64 s[24:25], 0
	s_mov_b64 s[26:27], -1
	s_waitcnt vmcnt(0) lgkmcnt(0)
	v_cmp_eq_u32_e32 vcc, 0, v2
	s_and_saveexec_b64 s[30:31], vcc
	s_cmp_lt_u32 s19, 0x400001
	s_cselect_b64 s[24:25], -1, 0
	s_xor_b64 s[26:27], exec, -1
	s_and_b64 s[24:25], s[24:25], exec
	s_or_b64 exec, exec, s[30:31]
.LBB0_1112:
	s_andn2_b64 s[20:21], s[20:21], exec
	s_and_b64 s[26:27], s[26:27], exec
	s_or_b64 s[20:21], s[20:21], s[26:27]
	s_and_saveexec_b64 s[26:27], s[24:25]
	s_cbranch_execz .LBB0_1107
	v_mov_b64_e32 v[2:3], s[12:13]
	global_load_dword v2, v[2:3], off sc1
	s_add_i32 s19, s19, 1
	s_or_b64 s[20:21], s[20:21], exec
	s_waitcnt vmcnt(0) lgkmcnt(0)
	v_cmp_ne_u32_e32 vcc, v2, v0
	s_orn2_b64 s[22:23], vcc, exec
	s_branch .LBB0_1107
.LBB0_1114:
	s_or_b64 exec, exec, s[14:15]
	s_xor_b64 s[12:13], s[16:17], -1
	s_and_saveexec_b64 s[14:15], s[12:13]
	s_xor_b64 s[14:15], exec, s[14:15]
	s_cbranch_execz .LBB0_1116
	v_mov_b64_e32 v[2:3], s[6:7]
	global_atomic_add v[2:3], v234, off offset:512

.LBB0_1117:
	s_andn2_saveexec_b64 s[8:9], s[8:9]
	s_cbranch_execz .LBB0_1134
	v_mov_b32_e32 v3, s6
	v_add_co_u32_e32 v4, vcc, 0x3000, v3
	v_mov_b32_e32 v3, s7
	buffer_wbl2 sc1
	s_waitcnt vmcnt(0) lgkmcnt(0)
	s_waitcnt vmcnt(0)
	v_addc_co_u32_e32 v5, vcc, 0, v3, vcc
	global_atomic_add v3, v[4:5], v234, off offset:1024 sc0
	v_cvt_f32_u32_e32 v4, v2
	v_sub_u32_e32 v5, 0, v2
	v_rcp_iflag_f32_e32 v4, v4
	s_nop 0
	v_mul_f32_e32 v4, 0x4f7ffffe, v4
	v_cvt_u32_f32_e32 v4, v4
	v_mul_lo_u32 v5, v5, v4
	v_mul_hi_u32 v5, v4, v5
	v_add_u32_e32 v4, v4, v5
	s_waitcnt vmcnt(0) lgkmcnt(0)
	v_mul_hi_u32 v4, v3, v4
	v_mul_lo_u32 v5, v4, v2
	v_sub_u32_e32 v5, v3, v5
	v_add_u32_e32 v6, 1, v4
	v_cmp_ge_u32_e32 vcc, v5, v2
	v_add_u32_e32 v3, 1, v3
	s_nop 0
	v_cndmask_b32_e32 v4, v4, v6, vcc
	v_sub_u32_e32 v6, v5, v2
	v_cndmask_b32_e32 v5, v5, v6, vcc
	v_add_u32_e32 v6, 1, v4
	v_cmp_ge_u32_e32 vcc, v5, v2
	s_nop 1
	v_cndmask_b32_e32 v4, v4, v6, vcc
	v_mul_lo_u32 v4, v2, v4
	v_add_u32_e32 v2, v4, v2
	v_cmp_ne_u32_e32 vcc, v3, v2
	s_and_saveexec_b64 s[8:9], vcc
	s_xor_b64 s[8:9], exec, s[8:9]
	s_cbranch_execz .LBB0_1131
	s_add_i32 s46, s18, 0x900
	s_lshl_b64 s[10:11], s[46:47], 2
	s_add_u32 s12, s6, s10
	s_addc_u32 s13, s7, s11
	v_mov_b64_e32 v[2:3], s[12:13]
	buffer_inv sc1
	global_load_dword v2, v[2:3], off sc1
	s_waitcnt vmcnt(0) lgkmcnt(0)
	v_cmp_eq_u32_e32 vcc, v2, v0
	s_and_saveexec_b64 s[10:11], vcc
	s_cbranch_execz .LBB0_1130
	s_mov_b32 s18, 1
	s_mov_b64 s[14:15], 0
	s_branch .LBB0_1122

.LBB0_1122:
	s_and_b32 s19, s18, 0xff
	s_mov_b64 s[22:23], -1
	s_cmp_lg_u32 s19, 0
	s_mov_b64 s[24:25], -1
	s_sleep 1
	s_cbranch_scc1 .LBB0_1126
	v_mov_b64_e32 v[2:3], s[6:7]
	global_load_dword v2, v[2:3], off offset:512 sc1
	s_mov_b64 s[24:25], 0
	s_mov_b64 s[26:27], -1
	s_waitcnt vmcnt(0) lgkmcnt(0)
	v_cmp_eq_u32_e32 vcc, 0, v2
	s_and_saveexec_b64 s[30:31], vcc
	s_cmp_lt_u32 s18, 0x400001
	s_cselect_b64 s[24:25], -1, 0
	s_xor_b64 s[26:27], exec, -1
	s_and_b64 s[24:25], s[24:25], exec
	s_or_b64 exec, exec, s[30:31]
.LBB0_1126:
	s_andn2_b64 s[20:21], s[20:21], exec
	s_and_b64 s[26:27], s[26:27], exec
	s_or_b64 s[20:21], s[20:21], s[26:27]
	s_and_saveexec_b64 s[26:27], s[24:25]
	s_cbranch_execz .LBB0_1121
	v_mov_b64_e32 v[2:3], s[12:13]
	global_load_dword v2, v[2:3], off sc1
	s_add_i32 s18, s18, 1
	s_or_b64 s[20:21], s[20:21], exec
	s_waitcnt vmcnt(0) lgkmcnt(0)
	v_cmp_ne_u32_e32 vcc, v2, v0
	s_orn2_b64 s[22:23], vcc, exec
	s_branch .LBB0_1121

.LBB0_1131:
	s_andn2_saveexec_b64 s[8:9], s[8:9]
	s_cbranch_execz .LBB0_1133
	v_mov_b32_e32 v0, s6
	v_add_co_u32_e32 v2, vcc, 0x2000, v0
	v_mov_b32_e32 v4, s7
	s_nop 0
	v_addc_co_u32_e32 v3, vcc, 0, v4, vcc
	global_atomic_add v[2:3], v234, off offset:1024
	global_atomic_add v[2:3], v234, off offset:1280
	global_atomic_add v[2:3], v234, off offset:1536
	global_atomic_add v[2:3], v234, off offset:1792
	global_atomic_add v[2:3], v234, off offset:2048
	global_atomic_add v[2:3], v234, off offset:2304
	global_atomic_add v[2:3], v234, off offset:2560
	global_atomic_add v[2:3], v234, off offset:2816
	global_atomic_add v[2:3], v234, off offset:3072
	global_atomic_add v[2:3], v234, off offset:3328
	global_atomic_add v[2:3], v234, off offset:3584
	global_atomic_add v[2:3], v234, off offset:3840
	v_add_co_u32_e32 v2, vcc, 0x3000, v0
	s_nop 1
	v_addc_co_u32_e32 v3, vcc, 0, v4, vcc
	global_atomic_add v[2:3], v234, off
	global_atomic_add v[2:3], v234, off offset:256
	global_atomic_add v[2:3], v234, off offset:512
	global_atomic_add v[2:3], v234, off offset:768
	s_waitcnt vmcnt(0) lgkmcnt(0)
	buffer_inv sc1

.LBB0_1198:
	v_readlane_b32 s2, v254, 1
	v_readlane_b32 s4, v254, 3
	v_readlane_b32 s3, v254, 2
	s_lshl_b32 s18, s4, 6
	v_readlane_b32 s5, v254, 4
	s_add_i32 s46, s18, 0x500
	s_waitcnt vmcnt(0) expcnt(0) lgkmcnt(0)
	v_mov_b32_e32 v0, s5
	s_lshl_b64 s[4:5], s[46:47], 2
	s_add_u32 s4, s2, s4
	s_addc_u32 s5, s3, s5
	v_mov_b64_e32 v[4:5], s[4:5]
	ds_read_b32 v3, v0
	ds_read_b32 v2, v0 offset:4
	global_atomic_add v4, v[4:5], v234, off sc0
	s_waitcnt lgkmcnt(0)
	v_cvt_f32_u32_e32 v0, v3
	v_sub_u32_e32 v5, 0, v3
	v_rcp_iflag_f32_e32 v0, v0
	s_nop 0
	v_mul_f32_e32 v0, 0x4f7ffffe, v0
	v_cvt_u32_f32_e32 v0, v0
	v_mul_lo_u32 v5, v5, v0
	v_mul_hi_u32 v5, v0, v5
	v_add_u32_e32 v0, v0, v5
	s_waitcnt vmcnt(0)
	v_mul_hi_u32 v0, v4, v0
	v_mul_lo_u32 v5, v0, v3
	v_sub_u32_e32 v5, v4, v5
	v_add_u32_e32 v6, 1, v0
	v_cmp_ge_u32_e32 vcc, v5, v3
	v_add_u32_e32 v4, 1, v4
	s_nop 0
	v_cndmask_b32_e32 v0, v0, v6, vcc
	v_sub_u32_e32 v6, v5, v3
	v_cndmask_b32_e32 v5, v5, v6, vcc
	v_add_u32_e32 v6, 1, v0
	v_cmp_ge_u32_e32 vcc, v5, v3
	s_nop 1
	v_cndmask_b32_e32 v0, v0, v6, vcc
	v_mul_lo_u32 v5, v3, v0
	v_add_u32_e32 v3, v5, v3
	v_cmp_ne_u32_e32 vcc, v4, v3
	s_and_saveexec_b64 s[4:5], vcc
	s_xor_b64 s[4:5], exec, s[4:5]
	s_cbranch_execz .LBB0_1211
	s_add_i32 s46, s18, 0x900
	s_lshl_b64 s[6:7], s[46:47], 2
	s_add_u32 s8, s2, s6
	s_addc_u32 s9, s3, s7
	v_mov_b64_e32 v[2:3], s[8:9]
	buffer_inv sc1
	global_load_dword v2, v[2:3], off sc1
	s_waitcnt vmcnt(0) lgkmcnt(0)
	v_cmp_eq_u32_e32 vcc, v2, v0
	s_and_saveexec_b64 s[6:7], vcc
	s_cbranch_execz .LBB0_1210
	s_mov_b32 s19, 1
	s_mov_b64 s[10:11], 0
	s_branch .LBB0_1202

.LBB0_1212:
	v_mov_b32_e32 v3, s2
	v_add_co_u32_e32 v4, vcc, 0x3000, v3
	v_mov_b32_e32 v3, s3
	buffer_wbl2 sc1
	s_waitcnt vmcnt(0) lgkmcnt(0)
	s_waitcnt vmcnt(0)
	v_addc_co_u32_e32 v5, vcc, 0, v3, vcc
	global_atomic_add v3, v[4:5], v234, off offset:1024 sc0
	v_cvt_f32_u32_e32 v4, v2
	v_sub_u32_e32 v5, 0, v2
	v_rcp_iflag_f32_e32 v4, v4
	s_nop 0
	v_mul_f32_e32 v4, 0x4f7ffffe, v4
	v_cvt_u32_f32_e32 v4, v4
	v_mul_lo_u32 v5, v5, v4
	v_mul_hi_u32 v5, v4, v5
	v_add_u32_e32 v4, v4, v5
	s_waitcnt vmcnt(0) lgkmcnt(0)
	v_mul_hi_u32 v4, v3, v4
	v_mul_lo_u32 v5, v4, v2
	v_sub_u32_e32 v5, v3, v5
	v_add_u32_e32 v6, 1, v4
	v_cmp_ge_u32_e32 vcc, v5, v2
	v_add_u32_e32 v3, 1, v3
	s_nop 0
	v_cndmask_b32_e32 v4, v4, v6, vcc
	v_sub_u32_e32 v6, v5, v2
	v_cndmask_b32_e32 v5, v5, v6, vcc
	v_add_u32_e32 v6, 1, v4
	v_cmp_ge_u32_e32 vcc, v5, v2
	s_nop 1
	v_cndmask_b32_e32 v4, v4, v6, vcc
	v_mul_lo_u32 v4, v2, v4
	v_add_u32_e32 v2, v4, v2
	v_cmp_ne_u32_e32 vcc, v3, v2
	s_and_saveexec_b64 s[4:5], vcc
	s_xor_b64 s[4:5], exec, s[4:5]
	s_cbranch_execz .LBB0_1225
	s_add_i32 s46, s18, 0x900
	s_lshl_b64 s[6:7], s[46:47], 2
	s_add_u32 s8, s2, s6
	s_addc_u32 s9, s3, s7
	v_mov_b64_e32 v[2:3], s[8:9]
	buffer_inv sc1
	global_load_dword v2, v[2:3], off sc1
	s_waitcnt vmcnt(0) lgkmcnt(0)
	v_cmp_eq_u32_e32 vcc, v2, v0
	s_and_saveexec_b64 s[6:7], vcc
	s_cbranch_execz .LBB0_1224
	s_mov_b32 s18, 1
	s_mov_b64 s[10:11], 0
	s_branch .LBB0_1216

.LBB0_1226:
	v_mov_b32_e32 v0, s2
	v_add_co_u32_e32 v2, vcc, 0x2000, v0
	v_mov_b32_e32 v4, s3
	s_nop 0
	v_addc_co_u32_e32 v3, vcc, 0, v4, vcc
	global_atomic_add v[2:3], v234, off offset:1024
	global_atomic_add v[2:3], v234, off offset:1280
	global_atomic_add v[2:3], v234, off offset:1536
	global_atomic_add v[2:3], v234, off offset:1792
	global_atomic_add v[2:3], v234, off offset:2048
	global_atomic_add v[2:3], v234, off offset:2304
	global_atomic_add v[2:3], v234, off offset:2560
	global_atomic_add v[2:3], v234, off offset:2816
	global_atomic_add v[2:3], v234, off offset:3072
	global_atomic_add v[2:3], v234, off offset:3328
	global_atomic_add v[2:3], v234, off offset:3584
	global_atomic_add v[2:3], v234, off offset:3840
	v_add_co_u32_e32 v2, vcc, 0x3000, v0
	s_nop 1
	v_addc_co_u32_e32 v3, vcc, 0, v4, vcc
	global_atomic_add v[2:3], v234, off
	global_atomic_add v[2:3], v234, off offset:256
	global_atomic_add v[2:3], v234, off offset:512
	global_atomic_add v[2:3], v234, off offset:768
	s_waitcnt vmcnt(0) lgkmcnt(0)
	buffer_inv sc1
	s_getpc_b64 s[98:99]
